# sb_attn cached-KV tiles load a half tile at once; adaLN GEMV k-loop rewritten by hand with next 16 weight rows prefetched during the multiply (f32 fma, same math)
# speedup vs baseline: 1.0321x; 1.0321x over previous
; #define LAS __attribute__((address_space(3)))
; __device__ __forceinline__ void prologue_phase(KA A, LAS unsigned char* lds, int tid, int lane, int wave) {
;     ...
;             const float* W = A->in[11] + (size_t)l * 1024 * 6144 + cg0 + lane;
;             float acc[NBB];
; #pragma unroll
;             for (int b = 0; b < NBB; ++b) acc[b] = 0.f;
;             const int kb = wave * 128;
; #pragma unroll 4
;             for (int k4 = 0; k4 < 128; k4 += 4) {
;                 const float w0 = W[(size_t)(kb + k4) * 6144], w1 = W[(size_t)(kb + k4 + 1) * 6144], w2 = W[(size_t)(kb + k4 + 2) * 6144], w3 = W[(size_t)(kb + k4 + 3) * 6144];
; #pragma unroll
;                 for (int b = 0; b < NBB; ++b) { const f32x4 s = *(const LAS f32x4*)(sc + b * 1024 + kb + k4); acc[b] += s.x * w0 + s.y * w1 + s.z * w2 + s.w * w3; }
;             }
.Lgemv_entry:
	v_add_co_u32_e32 v40, vcc, s27, v20
	s_mov_b64 s[46:47], 0x6000
	s_nop 0
	v_addc_co_u32_e32 v41, vcc, -1, v21, vcc
	global_load_dword v56, v[40:41], off
	v_lshl_add_u64 v[40:41], v[40:41], 0, s[46:47]
	global_load_dword v57, v[40:41], off
	v_lshl_add_u64 v[40:41], v[40:41], 0, s[46:47]
	global_load_dword v58, v[40:41], off
	v_lshl_add_u64 v[40:41], v[40:41], 0, s[46:47]
	global_load_dword v59, v[40:41], off
	v_lshl_add_u64 v[40:41], v[40:41], 0, s[46:47]
	global_load_dword v60, v[40:41], off
	v_lshl_add_u64 v[40:41], v[40:41], 0, s[46:47]
	global_load_dword v61, v[40:41], off
	v_lshl_add_u64 v[40:41], v[40:41], 0, s[46:47]
	global_load_dword v62, v[40:41], off
	v_lshl_add_u64 v[40:41], v[40:41], 0, s[46:47]
	global_load_dword v63, v[40:41], off
	v_lshl_add_u64 v[40:41], v[40:41], 0, s[46:47]
	global_load_dword v64, v[40:41], off
	v_lshl_add_u64 v[40:41], v[40:41], 0, s[46:47]
	global_load_dword v65, v[40:41], off
	v_lshl_add_u64 v[40:41], v[40:41], 0, s[46:47]
	global_load_dword v66, v[40:41], off
	v_lshl_add_u64 v[40:41], v[40:41], 0, s[46:47]
	global_load_dword v67, v[40:41], off
	v_lshl_add_u64 v[40:41], v[40:41], 0, s[46:47]
	global_load_dword v68, v[40:41], off
	v_lshl_add_u64 v[40:41], v[40:41], 0, s[46:47]
	global_load_dword v69, v[40:41], off
	v_lshl_add_u64 v[40:41], v[40:41], 0, s[46:47]
	global_load_dword v70, v[40:41], off
	v_lshl_add_u64 v[40:41], v[40:41], 0, s[46:47]
	global_load_dword v71, v[40:41], off
	v_lshl_add_u64 v[40:41], v[40:41], 0, s[46:47]
.Lgemv_loop:
	s_cmpk_eq_i32 s25, 0x6c
	s_cbranch_scc1 .Lgemv_noload
	global_load_dword v72, v[40:41], off
	v_lshl_add_u64 v[40:41], v[40:41], 0, s[46:47]
	global_load_dword v73, v[40:41], off
	v_lshl_add_u64 v[40:41], v[40:41], 0, s[46:47]
	global_load_dword v74, v[40:41], off
	v_lshl_add_u64 v[40:41], v[40:41], 0, s[46:47]
	global_load_dword v75, v[40:41], off
	v_lshl_add_u64 v[40:41], v[40:41], 0, s[46:47]
	global_load_dword v76, v[40:41], off
	v_lshl_add_u64 v[40:41], v[40:41], 0, s[46:47]
	global_load_dword v77, v[40:41], off
	v_lshl_add_u64 v[40:41], v[40:41], 0, s[46:47]
	global_load_dword v78, v[40:41], off
	v_lshl_add_u64 v[40:41], v[40:41], 0, s[46:47]
	global_load_dword v79, v[40:41], off
	v_lshl_add_u64 v[40:41], v[40:41], 0, s[46:47]
	global_load_dword v80, v[40:41], off
	v_lshl_add_u64 v[40:41], v[40:41], 0, s[46:47]
	global_load_dword v81, v[40:41], off
	v_lshl_add_u64 v[40:41], v[40:41], 0, s[46:47]
	global_load_dword v82, v[40:41], off
	v_lshl_add_u64 v[40:41], v[40:41], 0, s[46:47]
	global_load_dword v83, v[40:41], off
	v_lshl_add_u64 v[40:41], v[40:41], 0, s[46:47]
	global_load_dword v84, v[40:41], off
	v_lshl_add_u64 v[40:41], v[40:41], 0, s[46:47]
	global_load_dword v85, v[40:41], off
	v_lshl_add_u64 v[40:41], v[40:41], 0, s[46:47]
	global_load_dword v86, v[40:41], off
	v_lshl_add_u64 v[40:41], v[40:41], 0, s[46:47]
	global_load_dword v87, v[40:41], off
	v_lshl_add_u64 v[40:41], v[40:41], 0, s[46:47]
.Lgemv_noload:
	v_mov_b32_e32 v38, s45
	v_add_u32_e32 v39, 0x10000, v38
	s_waitcnt vmcnt(16)
	ds_read_b128 v[0:3], v38
	ds_read_b128 v[4:7], v38 offset:4096
	ds_read_b128 v[8:11], v38 offset:8192
	ds_read_b128 v[42:45], v38 offset:12288
	ds_read_b128 v[46:49], v38 offset:16384
	ds_read_b128 v[88:91], v38 offset:20480
	s_waitcnt lgkmcnt(5)
	v_fma_f32 v22, v0, v56, v22
	v_fma_f32 v22, v1, v57, v22
	v_fma_f32 v22, v2, v58, v22
	v_fma_f32 v22, v3, v59, v22
	ds_read_b128 v[0:3], v38 offset:24576
	s_waitcnt lgkmcnt(5)
	v_fma_f32 v23, v4, v56, v23
	v_fma_f32 v23, v5, v57, v23
	v_fma_f32 v23, v6, v58, v23
	v_fma_f32 v23, v7, v59, v23
	ds_read_b128 v[4:7], v38 offset:28672
	s_waitcnt lgkmcnt(5)
	v_fma_f32 v24, v8, v56, v24
	v_fma_f32 v24, v9, v57, v24
	v_fma_f32 v24, v10, v58, v24
	v_fma_f32 v24, v11, v59, v24
	ds_read_b128 v[8:11], v38 offset:32768
	s_waitcnt lgkmcnt(5)
	v_fma_f32 v25, v42, v56, v25
	v_fma_f32 v25, v43, v57, v25
	v_fma_f32 v25, v44, v58, v25
	v_fma_f32 v25, v45, v59, v25
	ds_read_b128 v[42:45], v38 offset:36864
	s_waitcnt lgkmcnt(5)
	v_fma_f32 v26, v46, v56, v26
	v_fma_f32 v26, v47, v57, v26
	v_fma_f32 v26, v48, v58, v26
	v_fma_f32 v26, v49, v59, v26
	ds_read_b128 v[46:49], v38 offset:40960
	s_waitcnt lgkmcnt(5)
	v_fma_f32 v27, v88, v56, v27
	v_fma_f32 v27, v89, v57, v27
	v_fma_f32 v27, v90, v58, v27
	v_fma_f32 v27, v91, v59, v27
	ds_read_b128 v[88:91], v38 offset:45056
	s_waitcnt lgkmcnt(5)
	v_fma_f32 v28, v0, v56, v28
	v_fma_f32 v28, v1, v57, v28
	v_fma_f32 v28, v2, v58, v28
	v_fma_f32 v28, v3, v59, v28
	ds_read_b128 v[0:3], v38 offset:49152
	s_waitcnt lgkmcnt(5)
	v_fma_f32 v29, v4, v56, v29
	v_fma_f32 v29, v5, v57, v29
	v_fma_f32 v29, v6, v58, v29
	v_fma_f32 v29, v7, v59, v29
	ds_read_b128 v[4:7], v38 offset:53248
	s_waitcnt lgkmcnt(5)
	v_fma_f32 v30, v8, v56, v30
	v_fma_f32 v30, v9, v57, v30
	v_fma_f32 v30, v10, v58, v30
	v_fma_f32 v30, v11, v59, v30
	ds_read_b128 v[8:11], v38 offset:57344
	s_waitcnt lgkmcnt(5)
	v_fma_f32 v31, v42, v56, v31
	v_fma_f32 v31, v43, v57, v31
	v_fma_f32 v31, v44, v58, v31
	v_fma_f32 v31, v45, v59, v31
	ds_read_b128 v[42:45], v38 offset:61440
	s_waitcnt lgkmcnt(5)
	v_fma_f32 v32, v46, v56, v32
	v_fma_f32 v32, v47, v57, v32
	v_fma_f32 v32, v48, v58, v32
	v_fma_f32 v32, v49, v59, v32
	ds_read_b128 v[46:49], v39
	s_waitcnt lgkmcnt(5)
	v_fma_f32 v33, v88, v56, v33
	v_fma_f32 v33, v89, v57, v33
	v_fma_f32 v33, v90, v58, v33
	v_fma_f32 v33, v91, v59, v33
	ds_read_b128 v[88:91], v39 offset:4096
	s_waitcnt lgkmcnt(5)
	v_fma_f32 v34, v0, v56, v34
	v_fma_f32 v34, v1, v57, v34
	v_fma_f32 v34, v2, v58, v34
	v_fma_f32 v34, v3, v59, v34
	ds_read_b128 v[0:3], v38 offset:16
	s_waitcnt lgkmcnt(5)
; #define LAS __attribute__((address_space(3)))
; __device__ __forceinline__ void prologue_phase(KA A, LAS unsigned char* lds, int tid, int lane, int wave) {
;     ...
; #pragma unroll 4
;             for (int k4 = 0; k4 < 128; k4 += 4) {
;                 const float w0 = W[(size_t)(kb + k4) * 6144], w1 = W[(size_t)(kb + k4 + 1) * 6144], w2 = W[(size_t)(kb + k4 + 2) * 6144], w3 = W[(size_t)(kb + k4 + 3) * 6144];
; #pragma unroll
;                 for (int b = 0; b < NBB; ++b) { const f32x4 s = *(const LAS f32x4*)(sc + b * 1024 + kb + k4); acc[b] += s.x * w0 + s.y * w1 + s.z * w2 + s.w * w3; }
;             }
	v_fma_f32 v35, v4, v56, v35
	v_fma_f32 v35, v5, v57, v35
	v_fma_f32 v35, v6, v58, v35
	v_fma_f32 v35, v7, v59, v35
	ds_read_b128 v[4:7], v38 offset:4112
	s_waitcnt lgkmcnt(5)
	v_fma_f32 v36, v8, v56, v36
	v_fma_f32 v36, v9, v57, v36
	v_fma_f32 v36, v10, v58, v36
	v_fma_f32 v36, v11, v59, v36
	ds_read_b128 v[8:11], v38 offset:8208
	s_waitcnt lgkmcnt(5)
	v_fma_f32 v37, v42, v56, v37
	v_fma_f32 v37, v43, v57, v37
	v_fma_f32 v37, v44, v58, v37
	v_fma_f32 v37, v45, v59, v37
	ds_read_b128 v[42:45], v38 offset:12304
	s_waitcnt lgkmcnt(5)
	v_fma_f32 v50, v46, v56, v50
	v_fma_f32 v50, v47, v57, v50
	v_fma_f32 v50, v48, v58, v50
	v_fma_f32 v50, v49, v59, v50
	ds_read_b128 v[46:49], v38 offset:16400
	s_waitcnt lgkmcnt(5)
	v_fma_f32 v51, v88, v56, v51
	v_fma_f32 v51, v89, v57, v51
	v_fma_f32 v51, v90, v58, v51
	v_fma_f32 v51, v91, v59, v51
	ds_read_b128 v[88:91], v38 offset:20496
	s_waitcnt lgkmcnt(5)
	v_fma_f32 v22, v0, v60, v22
	v_fma_f32 v22, v1, v61, v22
	v_fma_f32 v22, v2, v62, v22
	v_fma_f32 v22, v3, v63, v22
	ds_read_b128 v[0:3], v38 offset:24592
	s_waitcnt lgkmcnt(5)
	v_fma_f32 v23, v4, v60, v23
	v_fma_f32 v23, v5, v61, v23
	v_fma_f32 v23, v6, v62, v23
	v_fma_f32 v23, v7, v63, v23
	ds_read_b128 v[4:7], v38 offset:28688
	s_waitcnt lgkmcnt(5)
	v_fma_f32 v24, v8, v60, v24
	v_fma_f32 v24, v9, v61, v24
	v_fma_f32 v24, v10, v62, v24
	v_fma_f32 v24, v11, v63, v24
	ds_read_b128 v[8:11], v38 offset:32784
	s_waitcnt lgkmcnt(5)
	v_fma_f32 v25, v42, v60, v25
	v_fma_f32 v25, v43, v61, v25
	v_fma_f32 v25, v44, v62, v25
	v_fma_f32 v25, v45, v63, v25
	ds_read_b128 v[42:45], v38 offset:36880
	s_waitcnt lgkmcnt(5)
	v_fma_f32 v26, v46, v60, v26
	v_fma_f32 v26, v47, v61, v26
	v_fma_f32 v26, v48, v62, v26
	v_fma_f32 v26, v49, v63, v26
	ds_read_b128 v[46:49], v38 offset:40976
	s_waitcnt lgkmcnt(5)
	v_fma_f32 v27, v88, v60, v27
	v_fma_f32 v27, v89, v61, v27
	v_fma_f32 v27, v90, v62, v27
	v_fma_f32 v27, v91, v63, v27
	ds_read_b128 v[88:91], v38 offset:45072
	s_waitcnt lgkmcnt(5)
	v_fma_f32 v28, v0, v60, v28
	v_fma_f32 v28, v1, v61, v28
	v_fma_f32 v28, v2, v62, v28
	v_fma_f32 v28, v3, v63, v28
	ds_read_b128 v[0:3], v38 offset:49168
	s_waitcnt lgkmcnt(5)
	v_fma_f32 v29, v4, v60, v29
	v_fma_f32 v29, v5, v61, v29
	v_fma_f32 v29, v6, v62, v29
	v_fma_f32 v29, v7, v63, v29
	ds_read_b128 v[4:7], v38 offset:53264
	s_waitcnt lgkmcnt(5)
	v_fma_f32 v30, v8, v60, v30
	v_fma_f32 v30, v9, v61, v30
	v_fma_f32 v30, v10, v62, v30
	v_fma_f32 v30, v11, v63, v30
	ds_read_b128 v[8:11], v38 offset:57360
	s_waitcnt lgkmcnt(5)
	v_fma_f32 v31, v42, v60, v31
	v_fma_f32 v31, v43, v61, v31
	v_fma_f32 v31, v44, v62, v31
	v_fma_f32 v31, v45, v63, v31
	ds_read_b128 v[42:45], v38 offset:61456
	s_waitcnt lgkmcnt(5)
	v_fma_f32 v32, v46, v60, v32
	v_fma_f32 v32, v47, v61, v32
	v_fma_f32 v32, v48, v62, v32
	v_fma_f32 v32, v49, v63, v32
	ds_read_b128 v[46:49], v39 offset:16
	s_waitcnt lgkmcnt(5)
	v_fma_f32 v33, v88, v60, v33
	v_fma_f32 v33, v89, v61, v33
	v_fma_f32 v33, v90, v62, v33
	v_fma_f32 v33, v91, v63, v33
	ds_read_b128 v[88:91], v39 offset:4112
	s_waitcnt lgkmcnt(5)
	v_fma_f32 v34, v0, v60, v34
	v_fma_f32 v34, v1, v61, v34
	v_fma_f32 v34, v2, v62, v34
	v_fma_f32 v34, v3, v63, v34
	ds_read_b128 v[0:3], v38 offset:32
	s_waitcnt lgkmcnt(5)
	v_fma_f32 v35, v4, v60, v35
	v_fma_f32 v35, v5, v61, v35
	v_fma_f32 v35, v6, v62, v35
	v_fma_f32 v35, v7, v63, v35
	ds_read_b128 v[4:7], v38 offset:4128
	s_waitcnt lgkmcnt(5)
	v_fma_f32 v36, v8, v60, v36
	v_fma_f32 v36, v9, v61, v36
	v_fma_f32 v36, v10, v62, v36
	v_fma_f32 v36, v11, v63, v36
	ds_read_b128 v[8:11], v38 offset:8224
	s_waitcnt lgkmcnt(5)
	v_fma_f32 v37, v42, v60, v37
	v_fma_f32 v37, v43, v61, v37
	v_fma_f32 v37, v44, v62, v37
	v_fma_f32 v37, v45, v63, v37
	ds_read_b128 v[42:45], v38 offset:12320
	s_waitcnt lgkmcnt(5)
	v_fma_f32 v50, v46, v60, v50
	v_fma_f32 v50, v47, v61, v50
	v_fma_f32 v50, v48, v62, v50
	v_fma_f32 v50, v49, v63, v50
	ds_read_b128 v[46:49], v38 offset:16416
	s_waitcnt lgkmcnt(5)
	v_fma_f32 v51, v88, v60, v51
	v_fma_f32 v51, v89, v61, v51
	v_fma_f32 v51, v90, v62, v51
	v_fma_f32 v51, v91, v63, v51
	ds_read_b128 v[88:91], v38 offset:20512
	s_waitcnt lgkmcnt(5)
	v_fma_f32 v22, v0, v64, v22
	v_fma_f32 v22, v1, v65, v22
	v_fma_f32 v22, v2, v66, v22
	v_fma_f32 v22, v3, v67, v22
	ds_read_b128 v[0:3], v38 offset:24608
	s_waitcnt lgkmcnt(5)
	v_fma_f32 v23, v4, v64, v23
	v_fma_f32 v23, v5, v65, v23
	v_fma_f32 v23, v6, v66, v23
	v_fma_f32 v23, v7, v67, v23
	ds_read_b128 v[4:7], v38 offset:28704
	s_waitcnt lgkmcnt(5)
	v_fma_f32 v24, v8, v64, v24
	v_fma_f32 v24, v9, v65, v24
	v_fma_f32 v24, v10, v66, v24
	v_fma_f32 v24, v11, v67, v24
	ds_read_b128 v[8:11], v38 offset:32800
	s_waitcnt lgkmcnt(5)
	v_fma_f32 v25, v42, v64, v25
	v_fma_f32 v25, v43, v65, v25
	v_fma_f32 v25, v44, v66, v25
	v_fma_f32 v25, v45, v67, v25
	ds_read_b128 v[42:45], v38 offset:36896
	s_waitcnt lgkmcnt(5)
	v_fma_f32 v26, v46, v64, v26
	v_fma_f32 v26, v47, v65, v26
	v_fma_f32 v26, v48, v66, v26
	v_fma_f32 v26, v49, v67, v26
	ds_read_b128 v[46:49], v38 offset:40992
	s_waitcnt lgkmcnt(5)
	v_fma_f32 v27, v88, v64, v27
	v_fma_f32 v27, v89, v65, v27
	v_fma_f32 v27, v90, v66, v27
	v_fma_f32 v27, v91, v67, v27
	ds_read_b128 v[88:91], v38 offset:45088
	s_waitcnt lgkmcnt(5)
	v_fma_f32 v28, v0, v64, v28
	v_fma_f32 v28, v1, v65, v28
	v_fma_f32 v28, v2, v66, v28
	v_fma_f32 v28, v3, v67, v28
	ds_read_b128 v[0:3], v38 offset:49184
	s_waitcnt lgkmcnt(5)
	v_fma_f32 v29, v4, v64, v29
	v_fma_f32 v29, v5, v65, v29
	v_fma_f32 v29, v6, v66, v29
	v_fma_f32 v29, v7, v67, v29
	ds_read_b128 v[4:7], v38 offset:53280
	s_waitcnt lgkmcnt(5)
; #define LAS __attribute__((address_space(3)))
; __device__ __forceinline__ void prologue_phase(KA A, LAS unsigned char* lds, int tid, int lane, int wave) {
;     ...
; #pragma unroll 4
;             for (int k4 = 0; k4 < 128; k4 += 4) {
;                 const float w0 = W[(size_t)(kb + k4) * 6144], w1 = W[(size_t)(kb + k4 + 1) * 6144], w2 = W[(size_t)(kb + k4 + 2) * 6144], w3 = W[(size_t)(kb + k4 + 3) * 6144];
; #pragma unroll
;                 for (int b = 0; b < NBB; ++b) { const f32x4 s = *(const LAS f32x4*)(sc + b * 1024 + kb + k4); acc[b] += s.x * w0 + s.y * w1 + s.z * w2 + s.w * w3; }
;             }
; #pragma unroll
;             for (int b = 0; b < NBB; ++b) red[(wave * NBB + b) * 64 + lane] = acc[b];
;             __syncthreads();
	v_fma_f32 v30, v8, v64, v30
	v_fma_f32 v30, v9, v65, v30
	v_fma_f32 v30, v10, v66, v30
	v_fma_f32 v30, v11, v67, v30
	ds_read_b128 v[8:11], v38 offset:57376
	s_waitcnt lgkmcnt(5)
	v_fma_f32 v31, v42, v64, v31
	v_fma_f32 v31, v43, v65, v31
	v_fma_f32 v31, v44, v66, v31
	v_fma_f32 v31, v45, v67, v31
	ds_read_b128 v[42:45], v38 offset:61472
	s_waitcnt lgkmcnt(5)
	v_fma_f32 v32, v46, v64, v32
	v_fma_f32 v32, v47, v65, v32
	v_fma_f32 v32, v48, v66, v32
	v_fma_f32 v32, v49, v67, v32
	ds_read_b128 v[46:49], v39 offset:32
	s_waitcnt lgkmcnt(5)
	v_fma_f32 v33, v88, v64, v33
	v_fma_f32 v33, v89, v65, v33
	v_fma_f32 v33, v90, v66, v33
	v_fma_f32 v33, v91, v67, v33
	ds_read_b128 v[88:91], v39 offset:4128
	s_waitcnt lgkmcnt(5)
	v_fma_f32 v34, v0, v64, v34
	v_fma_f32 v34, v1, v65, v34
	v_fma_f32 v34, v2, v66, v34
	v_fma_f32 v34, v3, v67, v34
	ds_read_b128 v[0:3], v38 offset:48
	s_waitcnt lgkmcnt(5)
	v_fma_f32 v35, v4, v64, v35
	v_fma_f32 v35, v5, v65, v35
	v_fma_f32 v35, v6, v66, v35
	v_fma_f32 v35, v7, v67, v35
	ds_read_b128 v[4:7], v38 offset:4144
	s_waitcnt lgkmcnt(5)
	v_fma_f32 v36, v8, v64, v36
	v_fma_f32 v36, v9, v65, v36
	v_fma_f32 v36, v10, v66, v36
	v_fma_f32 v36, v11, v67, v36
	ds_read_b128 v[8:11], v38 offset:8240
	s_waitcnt lgkmcnt(5)
	v_fma_f32 v37, v42, v64, v37
	v_fma_f32 v37, v43, v65, v37
	v_fma_f32 v37, v44, v66, v37
	v_fma_f32 v37, v45, v67, v37
	ds_read_b128 v[42:45], v38 offset:12336
	s_waitcnt lgkmcnt(5)
	v_fma_f32 v50, v46, v64, v50
	v_fma_f32 v50, v47, v65, v50
	v_fma_f32 v50, v48, v66, v50
	v_fma_f32 v50, v49, v67, v50
	ds_read_b128 v[46:49], v38 offset:16432
	s_waitcnt lgkmcnt(5)
	v_fma_f32 v51, v88, v64, v51
	v_fma_f32 v51, v89, v65, v51
	v_fma_f32 v51, v90, v66, v51
	v_fma_f32 v51, v91, v67, v51
	ds_read_b128 v[88:91], v38 offset:20528
	s_waitcnt lgkmcnt(5)
	v_fma_f32 v22, v0, v68, v22
	v_fma_f32 v22, v1, v69, v22
	v_fma_f32 v22, v2, v70, v22
	v_fma_f32 v22, v3, v71, v22
	ds_read_b128 v[0:3], v38 offset:24624
	s_waitcnt lgkmcnt(5)
	v_fma_f32 v23, v4, v68, v23
	v_fma_f32 v23, v5, v69, v23
	v_fma_f32 v23, v6, v70, v23
	v_fma_f32 v23, v7, v71, v23
	ds_read_b128 v[4:7], v38 offset:28720
	s_waitcnt lgkmcnt(5)
	v_fma_f32 v24, v8, v68, v24
	v_fma_f32 v24, v9, v69, v24
	v_fma_f32 v24, v10, v70, v24
	v_fma_f32 v24, v11, v71, v24
	ds_read_b128 v[8:11], v38 offset:32816
	s_waitcnt lgkmcnt(5)
	v_fma_f32 v25, v42, v68, v25
	v_fma_f32 v25, v43, v69, v25
	v_fma_f32 v25, v44, v70, v25
	v_fma_f32 v25, v45, v71, v25
	ds_read_b128 v[42:45], v38 offset:36912
	s_waitcnt lgkmcnt(5)
	v_fma_f32 v26, v46, v68, v26
	v_fma_f32 v26, v47, v69, v26
	v_fma_f32 v26, v48, v70, v26
	v_fma_f32 v26, v49, v71, v26
	ds_read_b128 v[46:49], v38 offset:41008
	s_waitcnt lgkmcnt(5)
	v_fma_f32 v27, v88, v68, v27
	v_fma_f32 v27, v89, v69, v27
	v_fma_f32 v27, v90, v70, v27
	v_fma_f32 v27, v91, v71, v27
	ds_read_b128 v[88:91], v38 offset:45104
	s_waitcnt lgkmcnt(5)
	v_fma_f32 v28, v0, v68, v28
	v_fma_f32 v28, v1, v69, v28
	v_fma_f32 v28, v2, v70, v28
	v_fma_f32 v28, v3, v71, v28
	ds_read_b128 v[0:3], v38 offset:49200
	s_waitcnt lgkmcnt(5)
	v_fma_f32 v29, v4, v68, v29
	v_fma_f32 v29, v5, v69, v29
	v_fma_f32 v29, v6, v70, v29
	v_fma_f32 v29, v7, v71, v29
	ds_read_b128 v[4:7], v38 offset:53296
	s_waitcnt lgkmcnt(5)
	v_fma_f32 v30, v8, v68, v30
	v_fma_f32 v30, v9, v69, v30
	v_fma_f32 v30, v10, v70, v30
	v_fma_f32 v30, v11, v71, v30
	ds_read_b128 v[8:11], v38 offset:57392
	s_waitcnt lgkmcnt(5)
	v_fma_f32 v31, v42, v68, v31
	v_fma_f32 v31, v43, v69, v31
	v_fma_f32 v31, v44, v70, v31
	v_fma_f32 v31, v45, v71, v31
	ds_read_b128 v[42:45], v38 offset:61488
	s_waitcnt lgkmcnt(5)
	v_fma_f32 v32, v46, v68, v32
	v_fma_f32 v32, v47, v69, v32
	v_fma_f32 v32, v48, v70, v32
	v_fma_f32 v32, v49, v71, v32
	ds_read_b128 v[46:49], v39 offset:48
	s_waitcnt lgkmcnt(5)
	v_fma_f32 v33, v88, v68, v33
	v_fma_f32 v33, v89, v69, v33
	v_fma_f32 v33, v90, v70, v33
	v_fma_f32 v33, v91, v71, v33
	ds_read_b128 v[88:91], v39 offset:4144
	s_waitcnt lgkmcnt(5)
	v_fma_f32 v34, v0, v68, v34
	v_fma_f32 v34, v1, v69, v34
	v_fma_f32 v34, v2, v70, v34
	v_fma_f32 v34, v3, v71, v34
	s_waitcnt lgkmcnt(4)
	v_fma_f32 v35, v4, v68, v35
	v_fma_f32 v35, v5, v69, v35
	v_fma_f32 v35, v6, v70, v35
	v_fma_f32 v35, v7, v71, v35
	s_waitcnt lgkmcnt(3)
	v_fma_f32 v36, v8, v68, v36
	v_fma_f32 v36, v9, v69, v36
	v_fma_f32 v36, v10, v70, v36
	v_fma_f32 v36, v11, v71, v36
	s_waitcnt lgkmcnt(2)
	v_fma_f32 v37, v42, v68, v37
	v_fma_f32 v37, v43, v69, v37
	v_fma_f32 v37, v44, v70, v37
	v_fma_f32 v37, v45, v71, v37
	s_waitcnt lgkmcnt(1)
	v_fma_f32 v50, v46, v68, v50
	v_fma_f32 v50, v47, v69, v50
	v_fma_f32 v50, v48, v70, v50
	v_fma_f32 v50, v49, v71, v50
	s_waitcnt lgkmcnt(0)
	v_fma_f32 v51, v88, v68, v51
	v_fma_f32 v51, v89, v69, v51
	v_fma_f32 v51, v90, v70, v51
	v_fma_f32 v51, v91, v71, v51
	s_waitcnt vmcnt(0)
	v_mov_b32_e32 v56, v72
	v_mov_b32_e32 v57, v73
	v_mov_b32_e32 v58, v74
	v_mov_b32_e32 v59, v75
	v_mov_b32_e32 v60, v76
	v_mov_b32_e32 v61, v77
	v_mov_b32_e32 v62, v78
	v_mov_b32_e32 v63, v79
	v_mov_b32_e32 v64, v80
	v_mov_b32_e32 v65, v81
	v_mov_b32_e32 v66, v82
	v_mov_b32_e32 v67, v83
	v_mov_b32_e32 v68, v84
	v_mov_b32_e32 v69, v85
	v_mov_b32_e32 v70, v86
	v_mov_b32_e32 v71, v87
	s_add_i32 s25, s25, 16
	s_add_i32 s45, s45, 64
	s_cmpk_gt_u32 s25, 0x7b
	s_cbranch_scc0 .Lgemv_loop
	s_mul_i32 s0, s44, 0x1800
	s_add_i32 s0, s0, s24
	v_or_b32_e32 v0, s0, v168
	v_mad_u64_u32 v[2:3], s[0:1], s44, 18, v[18:19]
	v_mov_b64_e32 v[4:5], s[22:23]
	v_ashrrev_i32_e32 v1, 31, v0
	v_mad_i64_i32 v[2:3], s[0:1], v2, s6, v[4:5]
	v_lshl_add_u64 v[0:1], v[0:1], 2, s[10:11]
	v_lshl_add_u64 v[2:3], v[16:17], 0, v[2:3]
	s_mov_b64 s[22:23], 0
	v_mov_b32_e32 v4, v54
	v_mov_b32_e32 v5, v53
	ds_write2st64_b32 v55, v22, v23 offset1:1
	ds_write2st64_b32 v55, v24, v25 offset0:2 offset1:3
	ds_write2st64_b32 v55, v26, v27 offset0:4 offset1:5
	ds_write2st64_b32 v55, v28, v29 offset0:6 offset1:7
	ds_write2st64_b32 v55, v30, v31 offset0:8 offset1:9
	ds_write2st64_b32 v55, v32, v33 offset0:10 offset1:11
	ds_write2st64_b32 v55, v34, v35 offset0:12 offset1:13
	ds_write2st64_b32 v55, v36, v37 offset0:14 offset1:15
	ds_write2st64_b32 v55, v50, v51 offset0:16 offset1:17
	s_waitcnt lgkmcnt(0)
	s_barrier

; __device__ __forceinline__ unsigned pk2(float lo, float hi) { return pg8::cvt_pk_bf16(lo, hi); }
; __device__ __forceinline__ void sb_attn_phase(KA A, int lane, int wave) {
;     ...
;                 const float* Kt = Kpast + (size_t)kb * 512; const float* Vt = Vpast + (size_t)kb * 512;
; #pragma unroll
;                 for (int d0 = 0; d0 < 4; ++d0) { const float* k0 = Kt + (size_t)r32 * 512 + h * 64 + d0 * 16 + hi * 8; const float* k1 = k0 + 32 * 512;
;                     kf[2 * d0] = cvt8(*(const f32x4*)k0, *(const f32x4*)(k0 + 4)); kf[2 * d0 + 1] = cvt8(*(const f32x4*)k1, *(const f32x4*)(k1 + 4)); }
; #pragma unroll
;                 for (int jj = 0; jj < 4; ++jj) { const float* vb = Vt + (size_t)(32 * (jj >> 1) + 16 * (jj & 1) + 4 * hi) * 512 + h * 64 + r32;
; #pragma unroll
;                     for (int dd = 0; dd < 2; ++dd) { const float* v = vb + 32 * dd;
;                         u32x4 vw; vw.x = pk2(v[0], v[512]); vw.y = pk2(v[1024], v[1536]); vw.z = pk2(v[8 * 512], v[9 * 512]); vw.w = pk2(v[10 * 512], v[11 * 512]);
;                         vf[2 * jj + dd] = __builtin_bit_cast(bf16x8, vw); } }
.LBB0_1029:
	s_andn2_b64 vcc, exec, s[10:11]
	s_cbranch_vccnz .LBB0_1026
	s_mov_b32 s97, s89
	s_lshl_b64 s[10:11], s[96:97], 11
	v_lshl_add_u64 v[48:49], v[158:159], 0, s[10:11]
	s_mov_b64 s[12:13], 0x10000
	v_lshl_add_u64 v[50:51], v[48:49], 0, s[12:13]
	v_lshl_add_u64 v[52:53], v[160:161], 0, s[10:11]
	global_load_dwordx4 v[32:35], v[48:49], off
	global_load_dwordx4 v[184:187], v[48:49], off offset:16
	global_load_dwordx4 v[36:39], v[50:51], off
	global_load_dwordx4 v[188:191], v[50:51], off offset:16
	global_load_dwordx4 v[112:115], v[48:49], off offset:64
	global_load_dwordx4 v[192:195], v[48:49], off offset:80
	global_load_dwordx4 v[116:119], v[50:51], off offset:64
	global_load_dwordx4 v[196:199], v[50:51], off offset:80
	global_load_dwordx4 v[124:127], v[48:49], off offset:128
	global_load_dwordx4 v[200:203], v[48:49], off offset:144
	global_load_dwordx4 v[120:123], v[50:51], off offset:128
	global_load_dwordx4 v[204:207], v[50:51], off offset:144
	global_load_dwordx4 v[132:135], v[48:49], off offset:192
	global_load_dwordx4 v[208:211], v[48:49], off offset:208
	global_load_dwordx4 v[128:131], v[50:51], off offset:192
	global_load_dwordx4 v[212:215], v[50:51], off offset:208
	s_mov_b64 s[12:13], 0x1000
	v_lshl_add_u64 v[40:41], v[52:53], 0, s[12:13]
	s_mov_b64 s[12:13], 0x5000
	v_lshl_add_u64 v[42:43], v[52:53], 0, s[12:13]
	s_mov_b64 s[12:13], 0x9000
	v_lshl_add_u64 v[44:45], v[52:53], 0, s[12:13]
	s_mov_b64 s[12:13], 0xd000
	v_lshl_add_u64 v[46:47], v[52:53], 0, s[12:13]
	global_load_dword v80, v[40:41], off offset:-4096
	global_load_dword v216, v[40:41], off offset:-2048
	global_load_dword v81, v[40:41], off
	global_load_dword v217, v[40:41], off offset:2048
	global_load_dword v82, v[42:43], off offset:-4096
	global_load_dword v218, v[42:43], off offset:-2048
	global_load_dword v83, v[42:43], off
	global_load_dword v219, v[42:43], off offset:2048
	global_load_dword v84, v[40:41], off offset:-3968
	global_load_dword v220, v[40:41], off offset:-1920
	global_load_dword v85, v[40:41], off offset:128
	global_load_dword v221, v[40:41], off offset:2176
	global_load_dword v86, v[42:43], off offset:-3968
	global_load_dword v222, v[42:43], off offset:-1920
	global_load_dword v87, v[42:43], off offset:128
	global_load_dword v223, v[42:43], off offset:2176
	global_load_dword v88, v[44:45], off offset:-4096
	global_load_dword v224, v[44:45], off offset:-2048
	global_load_dword v89, v[44:45], off
	global_load_dword v225, v[44:45], off offset:2048
	global_load_dword v90, v[46:47], off offset:-4096
	global_load_dword v226, v[46:47], off offset:-2048
	global_load_dword v91, v[46:47], off
	global_load_dword v227, v[46:47], off offset:2048
	global_load_dword v92, v[44:45], off offset:-3968
	global_load_dword v228, v[44:45], off offset:-1920
	global_load_dword v93, v[44:45], off offset:128
	global_load_dword v229, v[44:45], off offset:2176
	global_load_dword v94, v[46:47], off offset:-3968
	global_load_dword v230, v[46:47], off offset:-1920
	global_load_dword v95, v[46:47], off offset:128
	global_load_dword v231, v[46:47], off offset:2176
	s_waitcnt vmcnt(32)
	v_cvt_pk_bf16_f32 v32, v32, v33
	v_cvt_pk_bf16_f32 v33, v34, v35
	v_cvt_pk_bf16_f32 v34, v184, v185
	v_cvt_pk_bf16_f32 v35, v186, v187
	v_cvt_pk_bf16_f32 v36, v36, v37
	v_cvt_pk_bf16_f32 v37, v38, v39
	v_cvt_pk_bf16_f32 v38, v188, v189
	v_cvt_pk_bf16_f32 v39, v190, v191
	v_cvt_pk_bf16_f32 v112, v112, v113
	v_cvt_pk_bf16_f32 v113, v114, v115
	v_cvt_pk_bf16_f32 v114, v192, v193
	v_cvt_pk_bf16_f32 v115, v194, v195
	v_cvt_pk_bf16_f32 v116, v116, v117
	v_cvt_pk_bf16_f32 v117, v118, v119
	v_cvt_pk_bf16_f32 v118, v196, v197
	v_cvt_pk_bf16_f32 v119, v198, v199
	v_cvt_pk_bf16_f32 v124, v124, v125
	v_cvt_pk_bf16_f32 v125, v126, v127
	v_cvt_pk_bf16_f32 v126, v200, v201
	v_cvt_pk_bf16_f32 v127, v202, v203
	v_cvt_pk_bf16_f32 v120, v120, v121
	v_cvt_pk_bf16_f32 v121, v122, v123
	v_cvt_pk_bf16_f32 v122, v204, v205
	v_cvt_pk_bf16_f32 v123, v206, v207
	v_cvt_pk_bf16_f32 v132, v132, v133
	v_cvt_pk_bf16_f32 v133, v134, v135
	v_cvt_pk_bf16_f32 v134, v208, v209
	v_cvt_pk_bf16_f32 v135, v210, v211
	v_cvt_pk_bf16_f32 v128, v128, v129
	v_cvt_pk_bf16_f32 v129, v130, v131
	v_cvt_pk_bf16_f32 v130, v212, v213
	v_cvt_pk_bf16_f32 v131, v214, v215
	s_waitcnt vmcnt(16)
; __device__ __forceinline__ unsigned pk2(float lo, float hi) { return pg8::cvt_pk_bf16(lo, hi); }
; __device__ __forceinline__ void sb_attn_phase(KA A, int lane, int wave) {
;     ...
; #pragma unroll
;                 for (int jj = 0; jj < 4; ++jj) { const float* vb = Vt + (size_t)(32 * (jj >> 1) + 16 * (jj & 1) + 4 * hi) * 512 + h * 64 + r32;
; #pragma unroll
;                     for (int dd = 0; dd < 2; ++dd) { const float* v = vb + 32 * dd;
;                         u32x4 vw; vw.x = pk2(v[0], v[512]); vw.y = pk2(v[1024], v[1536]); vw.z = pk2(v[8 * 512], v[9 * 512]); vw.w = pk2(v[10 * 512], v[11 * 512]);
;                         vf[2 * jj + dd] = __builtin_bit_cast(bf16x8, vw); } }
	v_cvt_pk_bf16_f32 v80, v80, v216
	v_cvt_pk_bf16_f32 v81, v81, v217
	v_cvt_pk_bf16_f32 v82, v82, v218
	v_cvt_pk_bf16_f32 v83, v83, v219
	v_cvt_pk_bf16_f32 v84, v84, v220
	v_cvt_pk_bf16_f32 v85, v85, v221
	v_cvt_pk_bf16_f32 v86, v86, v222
	v_cvt_pk_bf16_f32 v87, v87, v223
	s_mov_b64 s[12:13], 0x11000
	v_lshl_add_u64 v[200:201], v[52:53], 0, s[12:13]
	s_mov_b64 s[12:13], 0x15000
	v_lshl_add_u64 v[202:203], v[52:53], 0, s[12:13]
	s_mov_b64 s[12:13], 0x19000
	v_lshl_add_u64 v[204:205], v[52:53], 0, s[12:13]
	s_mov_b64 s[12:13], 0x1d000
	v_lshl_add_u64 v[206:207], v[52:53], 0, s[12:13]
	global_load_dword v96, v[200:201], off offset:-4096
	global_load_dword v184, v[200:201], off offset:-2048
	global_load_dword v97, v[200:201], off
	global_load_dword v185, v[200:201], off offset:2048
	global_load_dword v98, v[202:203], off offset:-4096
	global_load_dword v186, v[202:203], off offset:-2048
	global_load_dword v99, v[202:203], off
	global_load_dword v187, v[202:203], off offset:2048
	global_load_dword v100, v[200:201], off offset:-3968
	global_load_dword v188, v[200:201], off offset:-1920
	global_load_dword v101, v[200:201], off offset:128
	global_load_dword v189, v[200:201], off offset:2176
	global_load_dword v102, v[202:203], off offset:-3968
	global_load_dword v190, v[202:203], off offset:-1920
	global_load_dword v103, v[202:203], off offset:128
	global_load_dword v191, v[202:203], off offset:2176
	global_load_dword v104, v[204:205], off offset:-4096
	global_load_dword v192, v[204:205], off offset:-2048
	global_load_dword v105, v[204:205], off
	global_load_dword v193, v[204:205], off offset:2048
	global_load_dword v106, v[206:207], off offset:-4096
	global_load_dword v194, v[206:207], off offset:-2048
	global_load_dword v107, v[206:207], off
	global_load_dword v195, v[206:207], off offset:2048
	global_load_dword v108, v[204:205], off offset:-3968
	global_load_dword v196, v[204:205], off offset:-1920
	global_load_dword v109, v[204:205], off offset:128
	global_load_dword v197, v[204:205], off offset:2176
	global_load_dword v110, v[206:207], off offset:-3968
	global_load_dword v198, v[206:207], off offset:-1920
	global_load_dword v111, v[206:207], off offset:128
	global_load_dword v199, v[206:207], off offset:2176
	s_waitcnt vmcnt(32)
	v_cvt_pk_bf16_f32 v88, v88, v224
	v_cvt_pk_bf16_f32 v89, v89, v225
	v_cvt_pk_bf16_f32 v90, v90, v226
	v_cvt_pk_bf16_f32 v91, v91, v227
	v_cvt_pk_bf16_f32 v92, v92, v228
	v_cvt_pk_bf16_f32 v93, v93, v229
	v_cvt_pk_bf16_f32 v94, v94, v230
	v_cvt_pk_bf16_f32 v95, v95, v231
	s_waitcnt vmcnt(0)
	v_cvt_pk_bf16_f32 v96, v96, v184
	v_cvt_pk_bf16_f32 v97, v97, v185
	v_cvt_pk_bf16_f32 v98, v98, v186
	v_cvt_pk_bf16_f32 v99, v99, v187
	v_cvt_pk_bf16_f32 v100, v100, v188
	v_cvt_pk_bf16_f32 v101, v101, v189
	v_cvt_pk_bf16_f32 v102, v102, v190
	v_cvt_pk_bf16_f32 v103, v103, v191
	v_cvt_pk_bf16_f32 v104, v104, v192
	v_cvt_pk_bf16_f32 v105, v105, v193
	v_cvt_pk_bf16_f32 v106, v106, v194
	v_cvt_pk_bf16_f32 v107, v107, v195
	v_cvt_pk_bf16_f32 v108, v108, v196
	v_cvt_pk_bf16_f32 v109, v109, v197
	v_cvt_pk_bf16_f32 v110, v110, v198
	v_cvt_pk_bf16_f32 v111, v111, v199
	s_branch .LBB0_1026
